# GEMM main loops (P1/P4/P5): 18 v_lshl_add_u64 pointer temps folded into SGPR-base form of global_load_lds
# speedup vs baseline: 1.0026x; 1.0026x over previous
; #define PG8_STAGE(bufoff, gbase, voff) do { _Pragma("unroll") for (int _i = 0; _i < 2; ++_i) \
;         __builtin_amdgcn_global_load_lds((const unsigned*)((const char*)(gbase) + (voff)[_i]), (PG8_LAS unsigned*)(lds + (bufoff) + ldsw + _i * 8192), 16, 0, 0); } while (0)
; #define PG8_LDA(dst, b, h) do { _Pragma("unroll") for (int m = 0; m < 4; ++m) _Pragma("unroll") for (int k = 0; k < 2; ++k) dst[m][k] = *(const PG8_LAS bf16x8*)(lds + PG8_SA(b, h) + aoff + m * 2048 + k * 1024); } while (0)
; #define PG8_LDB(dst, b, h) do { _Pragma("unroll") for (int n = 0; n < 2; ++n) _Pragma("unroll") for (int k = 0; k < 2; ++k) dst[n][k] = *(const PG8_LAS bf16x8*)(lds + PG8_SB(b, h) + boff + n * 2048 + k * 1024); } while (0)
; #define PG8_WAIT_V(n) asm volatile("s_waitcnt vmcnt(" #n ")" ::: "memory")
; #define PG8_WAIT_L(n) asm volatile("s_waitcnt lgkmcnt(" #n ")" ::: "memory")
; #define PG8_BAR __builtin_amdgcn_s_barrier()
; #define PG8_SCHED __builtin_amdgcn_sched_barrier(0)
; template <class Epi, class Sched, bool ALIGN_EPI = false, bool SP2 = false>
; __device__ __forceinline__ void gemm_phase(PG8_LAS unsigned char* lds, const Gemm g, const Sched& S, const Epi& E, const int wid_s) {
;     ...
;         for (int t = 0; t < nt; t += 2) {
;             const bool last = (t == nt - 2);
;             const char* a1 = cA + (size_t)(t + 1) * kstep;
;             const char* a2 = last ? nA : cA + (size_t)(t + 2) * kstep; const char* b2 = last ? nB : cB + (size_t)(t + 2) * kstep;
;             const char* a3 = a2 + kstep; const char* b3 = b2 + kstep;
;             if (last && has_next) S.a_ready(nxt);
;             if constexpr (Epi::HAS_MID) { if (t == Epi::MID_T) { asm volatile("" ::: "memory"); E.mid(acc, cur, wr, wc, fr, fq); asm volatile("" ::: "memory"); } }
;             if constexpr (SP2) {
;             PG8_LDB(B0, 0, 0); PG8_LDB(B1, 0, 1); PG8_SCHED; PG8_LDA(At, 0, 0); PG8_STAGE(PG8_SA(1, 1), a1 + hstepA, voffA);
;             PG8_WAIT_V(8); PG8_WAIT_L(0); PG8_BAR; PG8_MMA(0, 0, At, B0); PG8_MMA(0, 1, At, B1); PG8_BAR; PG8_SCHED;
;             PG8_LDA(At, 0, 1); PG8_STAGE(PG8_SB(0, 0), b2, voffB); PG8_STAGE(PG8_SB(0, 1), b2 + hstepB, voffB); PG8_STAGE(PG8_SA(0, 0), a2, voffA);
;             PG8_WAIT_V(8); PG8_WAIT_L(0); PG8_BAR; PG8_MMA(1, 0, At, B0); PG8_MMA(1, 1, At, B1); PG8_BAR; PG8_SCHED;
.LBB0_159:
	ds_read_b128 v[32:35], v169
	ds_read_b128 v[36:39], v169 offset:1024
	ds_read_b128 v[44:47], v169 offset:2048
	ds_read_b128 v[52:55], v169 offset:3072
	ds_read_b128 v[162:165], v170
	ds_read_b128 v[172:175], v170 offset:1024
	ds_read_b128 v[178:181], v170 offset:2048
	ds_read_b128 v[182:185], v170 offset:3072
	s_add_u32 s50, s0, 0xfffc0080
	s_addc_u32 s51, s1, -1
	s_cmp_eq_u32 s71, 12
	s_cselect_b32 s53, s7, s51
	s_cselect_b32 s52, s25, s50
	s_cselect_b32 s51, s23, s70
	s_cselect_b32 s50, s68, s69
	s_add_i32 m0, s49, 0xc000
	ds_read_b128 v[186:189], v171
	ds_read_b128 v[190:193], v171 offset:1024
	ds_read_b128 v[194:197], v171 offset:2048
	ds_read_b128 v[198:201], v171 offset:3072
	ds_read_b128 v[202:205], v171 offset:4096
	ds_read_b128 v[206:209], v171 offset:5120
	ds_read_b128 v[210:213], v171 offset:6144
	ds_read_b128 v[214:217], v171 offset:7168
	global_load_lds_dwordx4 v154, s[0:1]
	s_add_i32 m0, s49, 0xe000
	s_nop 0
	global_load_lds_dwordx4 v156, s[0:1]
	s_waitcnt vmcnt(8)
	s_waitcnt lgkmcnt(0)
	s_barrier
	s_setprio 1
	s_waitcnt lgkmcnt(0)
	v_mfma_f32_16x16x32_bf16 v[140:143], v[32:35], v[186:189], v[140:143]
	v_mfma_f32_16x16x32_bf16 v[136:139], v[44:47], v[186:189], v[136:139]
	v_mfma_f32_16x16x32_bf16 v[124:127], v[32:35], v[194:197], v[124:127]
	v_mfma_f32_16x16x32_bf16 v[120:123], v[44:47], v[194:197], v[120:123]
	v_mfma_f32_16x16x32_bf16 v[108:111], v[32:35], v[202:205], v[108:111]
	v_mfma_f32_16x16x32_bf16 v[104:107], v[44:47], v[202:205], v[104:107]
	v_mfma_f32_16x16x32_bf16 v[92:95], v[32:35], v[210:213], v[92:95]
	v_mfma_f32_16x16x32_bf16 v[88:91], v[44:47], v[210:213], v[88:91]
	v_mfma_f32_16x16x32_bf16 v[140:143], v[36:39], v[190:193], v[140:143]
	v_mfma_f32_16x16x32_bf16 v[136:139], v[52:55], v[190:193], v[136:139]
	v_mfma_f32_16x16x32_bf16 v[124:127], v[36:39], v[198:201], v[124:127]
	v_mfma_f32_16x16x32_bf16 v[120:123], v[52:55], v[198:201], v[120:123]
	v_mfma_f32_16x16x32_bf16 v[108:111], v[36:39], v[206:209], v[108:111]
	v_mfma_f32_16x16x32_bf16 v[104:107], v[52:55], v[206:209], v[104:107]
	v_mfma_f32_16x16x32_bf16 v[92:95], v[36:39], v[214:217], v[92:95]
	v_mfma_f32_16x16x32_bf16 v[88:91], v[52:55], v[214:217], v[88:91]
	s_setprio 0
	s_setprio 1
	v_mfma_f32_16x16x32_bf16 v[132:135], v[162:165], v[186:189], v[132:135]
	v_mfma_f32_16x16x32_bf16 v[128:131], v[178:181], v[186:189], v[128:131]
	v_mfma_f32_16x16x32_bf16 v[116:119], v[162:165], v[194:197], v[116:119]
	v_mfma_f32_16x16x32_bf16 v[112:115], v[178:181], v[194:197], v[112:115]
	v_mfma_f32_16x16x32_bf16 v[100:103], v[162:165], v[202:205], v[100:103]
	v_mfma_f32_16x16x32_bf16 v[96:99], v[178:181], v[202:205], v[96:99]
	v_mfma_f32_16x16x32_bf16 v[84:87], v[162:165], v[210:213], v[84:87]
	v_mfma_f32_16x16x32_bf16 v[80:83], v[178:181], v[210:213], v[80:83]
	v_mfma_f32_16x16x32_bf16 v[132:135], v[172:175], v[190:193], v[132:135]
	v_mfma_f32_16x16x32_bf16 v[128:131], v[182:185], v[190:193], v[128:131]
	v_mfma_f32_16x16x32_bf16 v[116:119], v[172:175], v[198:201], v[116:119]
	v_mfma_f32_16x16x32_bf16 v[112:115], v[182:185], v[198:201], v[112:115]
	v_mfma_f32_16x16x32_bf16 v[100:103], v[172:175], v[206:209], v[100:103]
	v_mfma_f32_16x16x32_bf16 v[96:99], v[182:185], v[206:209], v[96:99]
	v_mfma_f32_16x16x32_bf16 v[84:87], v[172:175], v[214:217], v[84:87]
	v_mfma_f32_16x16x32_bf16 v[80:83], v[182:185], v[214:217], v[80:83]
	s_setprio 0
	s_barrier
	s_add_i32 s77, s65, s54
	v_lshl_add_u64 v[218:219], s[50:51], 0, v[146:147]
	s_mov_b32 m0, s77
	ds_read_b128 v[186:189], v171 offset:16384
	ds_read_b128 v[190:193], v171 offset:17408
	ds_read_b128 v[194:197], v171 offset:18432
	ds_read_b128 v[198:201], v171 offset:19456
	ds_read_b128 v[202:205], v171 offset:20480
	ds_read_b128 v[206:209], v171 offset:21504
	ds_read_b128 v[210:213], v171 offset:22528
	ds_read_b128 v[214:217], v171 offset:23552
	global_load_lds_dwordx4 v[218:219], off
	s_add_i32 m0, s77, 0x2000
	s_add_u32 s78, s50, 0x40000
	v_lshl_add_u64 v[220:221], s[50:51], 0, v[150:151]
	s_addc_u32 s79, s51, 0
	s_add_i32 s77, s66, s54
	global_load_lds_dwordx4 v[220:221], off
	s_mov_b32 m0, s77
	v_lshl_add_u64 v[224:225], s[52:53], 0, v[148:149]
	global_load_lds_dwordx4 v146, s[78:79]
	s_add_i32 m0, s77, 0x2000
	s_nop 0
	global_load_lds_dwordx4 v150, s[78:79]
	v_lshl_add_u64 v[222:223], s[52:53], 0, v[144:145]
	s_mov_b32 m0, s49
	s_nop 0
	global_load_lds_dwordx4 v[222:223], off
	s_mov_b32 m0, s55
	s_nop 0
	global_load_lds_dwordx4 v[224:225], off
	s_waitcnt vmcnt(8)
	s_waitcnt lgkmcnt(0)
	s_barrier
	s_setprio 1
	s_waitcnt lgkmcnt(0)
	v_mfma_f32_16x16x32_bf16 v[76:79], v[32:35], v[186:189], v[76:79]
	v_mfma_f32_16x16x32_bf16 v[72:75], v[44:47], v[186:189], v[72:75]
	v_mfma_f32_16x16x32_bf16 v[60:63], v[32:35], v[194:197], v[60:63]
	v_mfma_f32_16x16x32_bf16 v[56:59], v[44:47], v[194:197], v[56:59]
	v_mfma_f32_16x16x32_bf16 v[28:31], v[32:35], v[202:205], v[28:31]
	v_mfma_f32_16x16x32_bf16 v[24:27], v[44:47], v[202:205], v[24:27]
	v_mfma_f32_16x16x32_bf16 v[12:15], v[32:35], v[210:213], v[12:15]
	v_mfma_f32_16x16x32_bf16 v[8:11], v[44:47], v[210:213], v[8:11]
	v_mfma_f32_16x16x32_bf16 v[76:79], v[36:39], v[190:193], v[76:79]
	v_mfma_f32_16x16x32_bf16 v[72:75], v[52:55], v[190:193], v[72:75]
	v_mfma_f32_16x16x32_bf16 v[60:63], v[36:39], v[198:201], v[60:63]
	v_mfma_f32_16x16x32_bf16 v[56:59], v[52:55], v[198:201], v[56:59]
	v_mfma_f32_16x16x32_bf16 v[28:31], v[36:39], v[206:209], v[28:31]
	v_mfma_f32_16x16x32_bf16 v[24:27], v[52:55], v[206:209], v[24:27]
	v_mfma_f32_16x16x32_bf16 v[12:15], v[36:39], v[214:217], v[12:15]
	v_mfma_f32_16x16x32_bf16 v[8:11], v[52:55], v[214:217], v[8:11]
	s_setprio 0
	s_setprio 1
	v_mfma_f32_16x16x32_bf16 v[40:43], v[178:181], v[194:197], v[40:43]
	v_mfma_f32_16x16x32_bf16 v[20:23], v[162:165], v[202:205], v[20:23]
	v_mfma_f32_16x16x32_bf16 v[16:19], v[178:181], v[202:205], v[16:19]
	v_mfma_f32_16x16x32_bf16 v[4:7], v[162:165], v[210:213], v[4:7]
	v_mfma_f32_16x16x32_bf16 v[0:3], v[178:181], v[210:213], v[0:3]
	v_mfma_f32_16x16x32_bf16 v[32:35], v[162:165], v[186:189], v[68:71]
	v_mfma_f32_16x16x32_bf16 v[36:39], v[178:181], v[186:189], v[64:67]
	v_mfma_f32_16x16x32_bf16 v[44:47], v[162:165], v[194:197], v[48:51]
	v_mfma_f32_16x16x32_bf16 v[40:43], v[182:185], v[198:201], v[40:43]
	v_mfma_f32_16x16x32_bf16 v[20:23], v[172:175], v[206:209], v[20:23]
	v_mfma_f32_16x16x32_bf16 v[16:19], v[182:185], v[206:209], v[16:19]
	v_mfma_f32_16x16x32_bf16 v[4:7], v[172:175], v[214:217], v[4:7]
	v_mfma_f32_16x16x32_bf16 v[0:3], v[182:185], v[214:217], v[0:3]
	v_mfma_f32_16x16x32_bf16 v[32:35], v[172:175], v[190:193], v[32:35]
	v_mfma_f32_16x16x32_bf16 v[36:39], v[182:185], v[190:193], v[36:39]
	v_mfma_f32_16x16x32_bf16 v[44:47], v[172:175], v[198:201], v[44:47]
	s_setprio 0
	s_barrier
; #define PG8_STAGE(bufoff, gbase, voff) do { _Pragma("unroll") for (int _i = 0; _i < 2; ++_i) \
;         __builtin_amdgcn_global_load_lds((const unsigned*)((const char*)(gbase) + (voff)[_i]), (PG8_LAS unsigned*)(lds + (bufoff) + ldsw + _i * 8192), 16, 0, 0); } while (0)
; #define PG8_LDA(dst, b, h) do { _Pragma("unroll") for (int m = 0; m < 4; ++m) _Pragma("unroll") for (int k = 0; k < 2; ++k) dst[m][k] = *(const PG8_LAS bf16x8*)(lds + PG8_SA(b, h) + aoff + m * 2048 + k * 1024); } while (0)
; #define PG8_LDB(dst, b, h) do { _Pragma("unroll") for (int n = 0; n < 2; ++n) _Pragma("unroll") for (int k = 0; k < 2; ++k) dst[n][k] = *(const PG8_LAS bf16x8*)(lds + PG8_SB(b, h) + boff + n * 2048 + k * 1024); } while (0)
; #define PG8_MMA(ai, bj, At, Bt) do { __builtin_amdgcn_s_setprio(1); _Pragma("unroll") for (int m = 0; m < 4; ++m) _Pragma("unroll") for (int n = 0; n < 2; ++n) _Pragma("unroll") for (int k = 0; k < 2; ++k) \
;         acc[ai][bj][m][n] = __builtin_amdgcn_mfma_f32_16x16x32_bf16(Bt[n][k], At[m][k], acc[ai][bj][m][n], 0, 0, 0); __builtin_amdgcn_s_setprio(0); } while (0)
; #define PG8_WAIT_V(n) asm volatile("s_waitcnt vmcnt(" #n ")" ::: "memory")
; #define PG8_WAIT_L(n) asm volatile("s_waitcnt lgkmcnt(" #n ")" ::: "memory")
; #define PG8_BAR __builtin_amdgcn_s_barrier()
; #define PG8_SCHED __builtin_amdgcn_sched_barrier(0)
; template <class Epi, class Sched, bool ALIGN_EPI = false, bool SP2 = false>
; __device__ __forceinline__ void gemm_phase(PG8_LAS unsigned char* lds, const Gemm g, const Sched& S, const Epi& E, const int wid_s) {
;     ...
;             PG8_LDB(B0, 1, 0); PG8_LDB(B1, 1, 1); PG8_SCHED; PG8_LDA(At, 1, 0); PG8_STAGE(PG8_SA(0, 1), a2 + hstepA, voffA);
;             PG8_WAIT_V(8); PG8_WAIT_L(0); PG8_BAR; PG8_MMA(0, 0, At, B0); PG8_MMA(0, 1, At, B1); PG8_BAR; PG8_SCHED;
	s_add_i32 s77, 0, 0x18000
	s_add_i32 s78, 0, 0x1c000
	v_add_u32_e32 v68, s77, v167
	v_add_u32_e32 v177, s78, v167
	ds_read_b128 v[48:51], v68
	ds_read_b128 v[52:55], v68 offset:1024
	ds_read_b128 v[64:67], v68 offset:2048
	ds_read_b128 v[68:71], v68 offset:3072
	ds_read_b128 v[162:165], v177
	ds_read_b128 v[172:175], v177 offset:1024
	ds_read_b128 v[178:181], v177 offset:2048
	ds_read_b128 v[182:185], v177 offset:3072
	s_add_u32 s52, s52, 0x40000
	s_addc_u32 s53, s53, 0
	s_mov_b32 m0, s56
	ds_read_b128 v[186:189], v171 offset:32768
	ds_read_b128 v[190:193], v171 offset:33792
	ds_read_b128 v[194:197], v171 offset:34816
	ds_read_b128 v[198:201], v171 offset:35840
	ds_read_b128 v[202:205], v171 offset:36864
	ds_read_b128 v[206:209], v171 offset:37888
	ds_read_b128 v[210:213], v171 offset:38912
	ds_read_b128 v[214:217], v171 offset:39936
	global_load_lds_dwordx4 v144, s[52:53]
	v_lshl_add_u64 v[226:227], s[52:53], 0, v[148:149]
	s_mov_b32 m0, s57
	s_nop 0
	global_load_lds_dwordx4 v[226:227], off
	s_waitcnt vmcnt(8)
	s_waitcnt lgkmcnt(0)
	s_barrier
	s_setprio 1
	s_waitcnt lgkmcnt(0)
	v_mfma_f32_16x16x32_bf16 v[140:143], v[48:51], v[186:189], v[140:143]
	v_mfma_f32_16x16x32_bf16 v[136:139], v[64:67], v[186:189], v[136:139]
	v_mfma_f32_16x16x32_bf16 v[124:127], v[48:51], v[194:197], v[124:127]
	v_mfma_f32_16x16x32_bf16 v[120:123], v[64:67], v[194:197], v[120:123]
	v_mfma_f32_16x16x32_bf16 v[108:111], v[48:51], v[202:205], v[108:111]
	v_mfma_f32_16x16x32_bf16 v[104:107], v[64:67], v[202:205], v[104:107]
	v_mfma_f32_16x16x32_bf16 v[92:95], v[48:51], v[210:213], v[92:95]
	v_mfma_f32_16x16x32_bf16 v[88:91], v[64:67], v[210:213], v[88:91]
	v_mfma_f32_16x16x32_bf16 v[140:143], v[52:55], v[190:193], v[140:143]
	v_mfma_f32_16x16x32_bf16 v[136:139], v[68:71], v[190:193], v[136:139]
	v_mfma_f32_16x16x32_bf16 v[124:127], v[52:55], v[198:201], v[124:127]
	v_mfma_f32_16x16x32_bf16 v[120:123], v[68:71], v[198:201], v[120:123]
	v_mfma_f32_16x16x32_bf16 v[108:111], v[52:55], v[206:209], v[108:111]
	v_mfma_f32_16x16x32_bf16 v[104:107], v[68:71], v[206:209], v[104:107]
	v_mfma_f32_16x16x32_bf16 v[92:95], v[52:55], v[214:217], v[92:95]
	v_mfma_f32_16x16x32_bf16 v[88:91], v[68:71], v[214:217], v[88:91]
	s_setprio 0
	s_setprio 1
	v_mfma_f32_16x16x32_bf16 v[132:135], v[162:165], v[186:189], v[132:135]
	v_mfma_f32_16x16x32_bf16 v[128:131], v[178:181], v[186:189], v[128:131]
	v_mfma_f32_16x16x32_bf16 v[116:119], v[162:165], v[194:197], v[116:119]
	v_mfma_f32_16x16x32_bf16 v[112:115], v[178:181], v[194:197], v[112:115]
	v_mfma_f32_16x16x32_bf16 v[100:103], v[162:165], v[202:205], v[100:103]
	v_mfma_f32_16x16x32_bf16 v[96:99], v[178:181], v[202:205], v[96:99]
	v_mfma_f32_16x16x32_bf16 v[84:87], v[162:165], v[210:213], v[84:87]
	v_mfma_f32_16x16x32_bf16 v[80:83], v[178:181], v[210:213], v[80:83]
	v_mfma_f32_16x16x32_bf16 v[132:135], v[172:175], v[190:193], v[132:135]
	v_mfma_f32_16x16x32_bf16 v[128:131], v[182:185], v[190:193], v[128:131]
	v_mfma_f32_16x16x32_bf16 v[116:119], v[172:175], v[198:201], v[116:119]
	v_mfma_f32_16x16x32_bf16 v[112:115], v[182:185], v[198:201], v[112:115]
	v_mfma_f32_16x16x32_bf16 v[100:103], v[172:175], v[206:209], v[100:103]
	v_mfma_f32_16x16x32_bf16 v[96:99], v[182:185], v[206:209], v[96:99]
	v_mfma_f32_16x16x32_bf16 v[84:87], v[172:175], v[214:217], v[84:87]
	v_mfma_f32_16x16x32_bf16 v[80:83], v[182:185], v[214:217], v[80:83]
	s_setprio 0
	s_barrier
; #define PG8_STAGE(bufoff, gbase, voff) do { _Pragma("unroll") for (int _i = 0; _i < 2; ++_i) \
;         __builtin_amdgcn_global_load_lds((const unsigned*)((const char*)(gbase) + (voff)[_i]), (PG8_LAS unsigned*)(lds + (bufoff) + ldsw + _i * 8192), 16, 0, 0); } while (0)
; #define PG8_LDA(dst, b, h) do { _Pragma("unroll") for (int m = 0; m < 4; ++m) _Pragma("unroll") for (int k = 0; k < 2; ++k) dst[m][k] = *(const PG8_LAS bf16x8*)(lds + PG8_SA(b, h) + aoff + m * 2048 + k * 1024); } while (0)
; #define PG8_MMA(ai, bj, At, Bt) do { __builtin_amdgcn_s_setprio(1); _Pragma("unroll") for (int m = 0; m < 4; ++m) _Pragma("unroll") for (int n = 0; n < 2; ++n) _Pragma("unroll") for (int k = 0; k < 2; ++k) \
;         acc[ai][bj][m][n] = __builtin_amdgcn_mfma_f32_16x16x32_bf16(Bt[n][k], At[m][k], acc[ai][bj][m][n], 0, 0, 0); __builtin_amdgcn_s_setprio(0); } while (0)
; #define PG8_WAIT_V(n) asm volatile("s_waitcnt vmcnt(" #n ")" ::: "memory")
; #define PG8_WAIT_L(n) asm volatile("s_waitcnt lgkmcnt(" #n ")" ::: "memory")
; #define PG8_BAR __builtin_amdgcn_s_barrier()
; #define PG8_SCHED __builtin_amdgcn_sched_barrier(0)
; template <class Epi, class Sched, bool ALIGN_EPI = false, bool SP2 = false>
; __device__ __forceinline__ void gemm_phase(PG8_LAS unsigned char* lds, const Gemm g, const Sched& S, const Epi& E, const int wid_s) {
;     ...
;             PG8_LDA(At, 1, 1); PG8_STAGE(PG8_SB(1, 0), b3, voffB); PG8_STAGE(PG8_SB(1, 1), b3 + hstepB, voffB); PG8_STAGE(PG8_SA(1, 0), a3, voffA);
;             PG8_WAIT_V(8); PG8_WAIT_L(0); PG8_BAR; PG8_MMA(1, 0, At, B0); PG8_MMA(1, 1, At, B1); PG8_BAR; PG8_SCHED;
;     __device__ __forceinline__ void operator()(const f32x4 (&acc)[2][2][4][2], const Unit& u, int wr, int wc, int fr, int fq) const {
;         const int pn = u.pn;
;         const int mode = (pn >= 16) ? 2 : (((pn >= 6 && pn < 10) || pn >= 14) ? 1 : 0);
;         const int row0 = u.pm * BM + wr * 64 + fr, col0 = pn * BM + wc * 32 + 8 * fq;
;         bf16_t* gt_b = GT + gt_off(u.pm, (pn - 16) & 7, wr * 4 + wc, 0, 0, 0, fq * 16 + fr);
;         f32x4 bv[2][2];
; #pragma unroll
;         for (int bj = 0; bj < 2; ++bj)
; #pragma unroll
;             for (int n = 0; n < 2; ++n) bv[bj][n] = (mode == 2) ? *(const f32x4*)(bias + (col0 - C_G) + bj * HALF + 4 * n) : (f32x4){0.f, 0.f, 0.f, 0.f};
	s_add_i32 s52, s77, s54
	v_lshl_add_u64 v[218:219], v[218:219], 0, s[16:17]
	s_mov_b32 m0, s52
	ds_read_b128 v[186:189], v171 offset:49152
	ds_read_b128 v[190:193], v171 offset:50176
	ds_read_b128 v[194:197], v171 offset:51200
	ds_read_b128 v[198:201], v171 offset:52224
	ds_read_b128 v[202:205], v171 offset:53248
	ds_read_b128 v[206:209], v171 offset:54272
	ds_read_b128 v[210:213], v171 offset:55296
	ds_read_b128 v[214:217], v171 offset:56320
	global_load_lds_dwordx4 v[218:219], off
	s_add_i32 m0, s52, 0x2000
	s_add_u32 s50, s50, 0x40080
	v_lshl_add_u64 v[218:219], v[220:221], 0, s[16:17]
	s_addc_u32 s51, s51, 0
	s_add_i32 s52, s78, s54
	global_load_lds_dwordx4 v[218:219], off
	s_mov_b32 m0, s52
	s_nop 0
	global_load_lds_dwordx4 v146, s[50:51]
	s_add_i32 m0, s52, 0x2000
	s_nop 0
	global_load_lds_dwordx4 v150, s[50:51]
	v_lshl_add_u64 v[218:219], v[222:223], 0, s[16:17]
	s_mov_b32 m0, s59
	s_nop 0
	global_load_lds_dwordx4 v[218:219], off
	v_lshl_add_u64 v[218:219], v[224:225], 0, s[16:17]
	s_mov_b32 m0, s60
	s_nop 0
	global_load_lds_dwordx4 v[218:219], off
	s_waitcnt vmcnt(8)
	s_waitcnt lgkmcnt(0)
	s_barrier
	s_setprio 1
	s_waitcnt lgkmcnt(0)
	v_mfma_f32_16x16x32_bf16 v[76:79], v[48:51], v[186:189], v[76:79]
	v_mfma_f32_16x16x32_bf16 v[72:75], v[64:67], v[186:189], v[72:75]
	v_mfma_f32_16x16x32_bf16 v[60:63], v[48:51], v[194:197], v[60:63]
	v_mfma_f32_16x16x32_bf16 v[56:59], v[64:67], v[194:197], v[56:59]
	v_mfma_f32_16x16x32_bf16 v[28:31], v[48:51], v[202:205], v[28:31]
	v_mfma_f32_16x16x32_bf16 v[24:27], v[64:67], v[202:205], v[24:27]
	v_mfma_f32_16x16x32_bf16 v[12:15], v[48:51], v[210:213], v[12:15]
	v_mfma_f32_16x16x32_bf16 v[8:11], v[64:67], v[210:213], v[8:11]
	v_mfma_f32_16x16x32_bf16 v[76:79], v[52:55], v[190:193], v[76:79]
	v_mfma_f32_16x16x32_bf16 v[72:75], v[68:71], v[190:193], v[72:75]
	v_mfma_f32_16x16x32_bf16 v[60:63], v[52:55], v[198:201], v[60:63]
	v_mfma_f32_16x16x32_bf16 v[56:59], v[68:71], v[198:201], v[56:59]
	v_mfma_f32_16x16x32_bf16 v[28:31], v[52:55], v[206:209], v[28:31]
	v_mfma_f32_16x16x32_bf16 v[24:27], v[68:71], v[206:209], v[24:27]
	v_mfma_f32_16x16x32_bf16 v[12:15], v[52:55], v[214:217], v[12:15]
	v_mfma_f32_16x16x32_bf16 v[8:11], v[68:71], v[214:217], v[8:11]
	s_setprio 0
	s_setprio 1
	v_mfma_f32_16x16x32_bf16 v[32:35], v[162:165], v[186:189], v[32:35]
	v_mfma_f32_16x16x32_bf16 v[68:71], v[172:175], v[190:193], v[32:35]
	v_mfma_f32_16x16x32_bf16 v[32:35], v[178:181], v[186:189], v[36:39]
	v_mfma_f32_16x16x32_bf16 v[64:67], v[182:185], v[190:193], v[32:35]
	v_mfma_f32_16x16x32_bf16 v[32:35], v[162:165], v[194:197], v[44:47]
	v_mfma_f32_16x16x32_bf16 v[48:51], v[172:175], v[198:201], v[32:35]
	v_mfma_f32_16x16x32_bf16 v[32:35], v[178:181], v[194:197], v[40:43]
	v_mfma_f32_16x16x32_bf16 v[20:23], v[162:165], v[202:205], v[20:23]
	v_mfma_f32_16x16x32_bf16 v[16:19], v[178:181], v[202:205], v[16:19]
	v_mfma_f32_16x16x32_bf16 v[4:7], v[162:165], v[210:213], v[4:7]
	v_mfma_f32_16x16x32_bf16 v[0:3], v[178:181], v[210:213], v[0:3]
	v_mfma_f32_16x16x32_bf16 v[40:43], v[182:185], v[198:201], v[32:35]
	v_mfma_f32_16x16x32_bf16 v[20:23], v[172:175], v[206:209], v[20:23]
	v_mfma_f32_16x16x32_bf16 v[16:19], v[182:185], v[206:209], v[16:19]
	v_mfma_f32_16x16x32_bf16 v[4:7], v[172:175], v[214:217], v[4:7]
	v_mfma_f32_16x16x32_bf16 v[0:3], v[182:185], v[214:217], v[0:3]
	s_setprio 0
	s_barrier
	s_add_i32 s71, s71, 2
	s_add_u32 s0, s0, 0x100
	s_addc_u32 s1, s1, 0
	s_add_u32 s69, s69, 0x100
	s_addc_u32 s70, s70, 0
	s_cmp_gt_u32 s71, 13
	s_cbranch_scc0 .LBB0_159
	s_cmp_gt_i32 s48, 15
	s_cselect_b64 s[52:53], -1, 0
	s_cmp_lt_i32 s48, 16
	s_cselect_b64 s[50:51], -1, 0
	v_lshl_or_b32 v162, s48, 8, v168
	v_mov_b32_e32 v163, v147
	v_lshl_add_u64 v[164:165], v[162:163], 2, s[36:37]
	v_mov_b32_e32 v44, 0
	s_and_b64 vcc, exec, s[50:51]
	v_mov_b32_e32 v52, 0
	v_mov_b32_e32 v53, 0
	v_mov_b32_e32 v54, 0
	v_mov_b32_e32 v55, 0
	s_cbranch_vccnz .LBB0_162
	v_add_co_u32_e32 v32, vcc, 0xffffc000, v164
	s_nop 1
	v_addc_co_u32_e32 v33, vcc, -1, v165, vcc
	global_load_dwordx4 v[52:55], v[32:33], off

; #define PG8_STAGE(bufoff, gbase, voff) do { _Pragma("unroll") for (int _i = 0; _i < 2; ++_i) \
;         __builtin_amdgcn_global_load_lds((const unsigned*)((const char*)(gbase) + (voff)[_i]), (PG8_LAS unsigned*)(lds + (bufoff) + ldsw + _i * 8192), 16, 0, 0); } while (0)
; #define PG8_LDA(dst, b, h) do { _Pragma("unroll") for (int m = 0; m < 4; ++m) _Pragma("unroll") for (int k = 0; k < 2; ++k) dst[m][k] = *(const PG8_LAS bf16x8*)(lds + PG8_SA(b, h) + aoff + m * 2048 + k * 1024); } while (0)
; #define PG8_LDB(dst, b, h) do { _Pragma("unroll") for (int n = 0; n < 2; ++n) _Pragma("unroll") for (int k = 0; k < 2; ++k) dst[n][k] = *(const PG8_LAS bf16x8*)(lds + PG8_SB(b, h) + boff + n * 2048 + k * 1024); } while (0)
; #define PG8_WAIT_V(n) asm volatile("s_waitcnt vmcnt(" #n ")" ::: "memory")
; #define PG8_WAIT_L(n) asm volatile("s_waitcnt lgkmcnt(" #n ")" ::: "memory")
; #define PG8_BAR __builtin_amdgcn_s_barrier()
; #define PG8_SCHED __builtin_amdgcn_sched_barrier(0)
; template <class Epi, class Sched, bool ALIGN_EPI = false, bool SP2 = false>
; __device__ __forceinline__ void gemm_phase(PG8_LAS unsigned char* lds, const Gemm g, const Sched& S, const Epi& E, const int wid_s) {
;     ...
;         for (int t = 0; t < nt; t += 2) {
;             const bool last = (t == nt - 2);
;             const char* a1 = cA + (size_t)(t + 1) * kstep;
;             const char* a2 = last ? nA : cA + (size_t)(t + 2) * kstep; const char* b2 = last ? nB : cB + (size_t)(t + 2) * kstep;
;             const char* a3 = a2 + kstep; const char* b3 = b2 + kstep;
;             if (last && has_next) S.a_ready(nxt);
;             if constexpr (Epi::HAS_MID) { if (t == Epi::MID_T) { asm volatile("" ::: "memory"); E.mid(acc, cur, wr, wc, fr, fq); asm volatile("" ::: "memory"); } }
;             if constexpr (SP2) {
;             PG8_LDB(B0, 0, 0); PG8_LDB(B1, 0, 1); PG8_SCHED; PG8_LDA(At, 0, 0); PG8_STAGE(PG8_SA(1, 1), a1 + hstepA, voffA);
;             PG8_WAIT_V(8); PG8_WAIT_L(0); PG8_BAR; PG8_MMA(0, 0, At, B0); PG8_MMA(0, 1, At, B1); PG8_BAR; PG8_SCHED;
;             PG8_LDA(At, 0, 1); PG8_STAGE(PG8_SB(0, 0), b2, voffB); PG8_STAGE(PG8_SB(0, 1), b2 + hstepB, voffB); PG8_STAGE(PG8_SA(0, 0), a2, voffA);
;             PG8_WAIT_V(8); PG8_WAIT_L(0); PG8_BAR; PG8_MMA(1, 0, At, B0); PG8_MMA(1, 1, At, B1); PG8_BAR; PG8_SCHED;
.LBB0_561:
	v_add_u32_e32 v1, s62, v189
	ds_read_b128 v[132:135], v1
	ds_read_b128 v[136:139], v1 offset:1024
	ds_read_b128 v[140:143], v1 offset:2048
	ds_read_b128 v[144:147], v1 offset:3072
	v_add_u32_e32 v1, s63, v189
	s_add_u32 s46, s24, s38
	ds_read_b128 v[148:151], v1
	ds_read_b128 v[152:155], v1 offset:1024
	ds_read_b128 v[156:159], v1 offset:2048
	ds_read_b128 v[182:185], v1 offset:3072
	s_addc_u32 s47, s25, s39
	s_add_u32 s46, s46, 0x100
	s_addc_u32 s47, s47, 0
	s_add_u32 s76, s69, s38
	s_addc_u32 s77, s70, s39
	s_cmpk_eq_i32 s38, 0xb00
	s_cselect_b32 s49, s1, s47
	s_cselect_b32 s48, s0, s46
	s_cselect_b32 s47, s23, s77
	s_cselect_b32 s46, s22, s76
	v_lshl_add_u64 v[2:3], v[178:179], 0, s[38:39]
	s_add_i32 m0, s51, 0xc000
	ds_read_b128 v[194:197], v192
	ds_read_b128 v[198:201], v192 offset:1024
	ds_read_b128 v[202:205], v192 offset:2048
	ds_read_b128 v[206:209], v192 offset:3072
	ds_read_b128 v[210:213], v192 offset:4096
	ds_read_b128 v[214:217], v192 offset:5120
	ds_read_b128 v[218:221], v192 offset:6144
	ds_read_b128 v[222:225], v192 offset:7168
	global_load_lds_dwordx4 v[2:3], off
	v_lshl_add_u64 v[2:3], v[180:181], 0, s[38:39]
	s_add_i32 m0, s51, 0xe000
	s_nop 0
	global_load_lds_dwordx4 v[2:3], off
	s_waitcnt vmcnt(8)
	s_waitcnt lgkmcnt(0)
	s_barrier
	s_setprio 1
	s_waitcnt lgkmcnt(0)
	v_mfma_f32_16x16x32_bf16 v[128:131], v[132:135], v[194:197], v[128:131]
	v_mfma_f32_16x16x32_bf16 v[124:127], v[140:143], v[194:197], v[124:127]
	v_mfma_f32_16x16x32_bf16 v[112:115], v[132:135], v[202:205], v[112:115]
	v_mfma_f32_16x16x32_bf16 v[108:111], v[140:143], v[202:205], v[108:111]
	v_mfma_f32_16x16x32_bf16 v[96:99], v[132:135], v[210:213], v[96:99]
	v_mfma_f32_16x16x32_bf16 v[92:95], v[140:143], v[210:213], v[92:95]
	v_mfma_f32_16x16x32_bf16 v[80:83], v[132:135], v[218:221], v[80:83]
	v_mfma_f32_16x16x32_bf16 v[76:79], v[140:143], v[218:221], v[76:79]
	v_mfma_f32_16x16x32_bf16 v[128:131], v[136:139], v[198:201], v[128:131]
	v_mfma_f32_16x16x32_bf16 v[124:127], v[144:147], v[198:201], v[124:127]
	v_mfma_f32_16x16x32_bf16 v[112:115], v[136:139], v[206:209], v[112:115]
	v_mfma_f32_16x16x32_bf16 v[108:111], v[144:147], v[206:209], v[108:111]
	v_mfma_f32_16x16x32_bf16 v[96:99], v[136:139], v[214:217], v[96:99]
	v_mfma_f32_16x16x32_bf16 v[92:95], v[144:147], v[214:217], v[92:95]
	v_mfma_f32_16x16x32_bf16 v[80:83], v[136:139], v[222:225], v[80:83]
	v_mfma_f32_16x16x32_bf16 v[76:79], v[144:147], v[222:225], v[76:79]
	s_setprio 0
	s_setprio 1
	v_mfma_f32_16x16x32_bf16 v[120:123], v[148:151], v[194:197], v[120:123]
	v_mfma_f32_16x16x32_bf16 v[116:119], v[156:159], v[194:197], v[116:119]
	v_mfma_f32_16x16x32_bf16 v[104:107], v[148:151], v[202:205], v[104:107]
	v_mfma_f32_16x16x32_bf16 v[100:103], v[156:159], v[202:205], v[100:103]
	v_mfma_f32_16x16x32_bf16 v[88:91], v[148:151], v[210:213], v[88:91]
	v_mfma_f32_16x16x32_bf16 v[84:87], v[156:159], v[210:213], v[84:87]
	v_mfma_f32_16x16x32_bf16 v[72:75], v[148:151], v[218:221], v[72:75]
	v_mfma_f32_16x16x32_bf16 v[68:71], v[156:159], v[218:221], v[68:71]
	v_mfma_f32_16x16x32_bf16 v[120:123], v[152:155], v[198:201], v[120:123]
	v_mfma_f32_16x16x32_bf16 v[116:119], v[182:185], v[198:201], v[116:119]
	v_mfma_f32_16x16x32_bf16 v[104:107], v[152:155], v[206:209], v[104:107]
	v_mfma_f32_16x16x32_bf16 v[100:103], v[182:185], v[206:209], v[100:103]
	v_mfma_f32_16x16x32_bf16 v[88:91], v[152:155], v[214:217], v[88:91]
	v_mfma_f32_16x16x32_bf16 v[84:87], v[182:185], v[214:217], v[84:87]
	v_mfma_f32_16x16x32_bf16 v[72:75], v[152:155], v[222:225], v[72:75]
	v_mfma_f32_16x16x32_bf16 v[68:71], v[182:185], v[222:225], v[68:71]
	s_setprio 0
	s_barrier
	s_add_i32 s76, s62, s50
	v_lshl_add_u64 v[160:161], s[46:47], 0, v[164:165]
	s_mov_b32 m0, s76
	ds_read_b128 v[194:197], v192 offset:16384
	ds_read_b128 v[198:201], v192 offset:17408
	ds_read_b128 v[202:205], v192 offset:18432
	ds_read_b128 v[206:209], v192 offset:19456
	ds_read_b128 v[210:213], v192 offset:20480
	ds_read_b128 v[214:217], v192 offset:21504
	ds_read_b128 v[218:221], v192 offset:22528
	ds_read_b128 v[222:225], v192 offset:23552
	global_load_lds_dwordx4 v[160:161], off
	s_add_i32 m0, s76, 0x2000
	s_add_u32 s76, s46, 0x60000
	v_lshl_add_u64 v[186:187], s[46:47], 0, v[168:169]
	s_addc_u32 s77, s47, 0
	s_add_i32 s78, s63, s50
	global_load_lds_dwordx4 v[186:187], off
	s_mov_b32 m0, s78
	v_lshl_add_u64 v[226:227], s[48:49], 0, v[162:163]
	global_load_lds_dwordx4 v164, s[76:77]
	s_add_i32 m0, s78, 0x2000
	v_lshl_add_u64 v[228:229], s[48:49], 0, v[166:167]
	global_load_lds_dwordx4 v168, s[76:77]
	s_mov_b32 m0, s51
	s_nop 0
	global_load_lds_dwordx4 v[226:227], off
	s_mov_b32 m0, s52
	s_nop 0
	global_load_lds_dwordx4 v[228:229], off
	s_waitcnt vmcnt(8)
	s_waitcnt lgkmcnt(0)
	s_barrier
; #define PG8_STAGE(bufoff, gbase, voff) do { _Pragma("unroll") for (int _i = 0; _i < 2; ++_i) \
;         __builtin_amdgcn_global_load_lds((const unsigned*)((const char*)(gbase) + (voff)[_i]), (PG8_LAS unsigned*)(lds + (bufoff) + ldsw + _i * 8192), 16, 0, 0); } while (0)
; #define PG8_LDA(dst, b, h) do { _Pragma("unroll") for (int m = 0; m < 4; ++m) _Pragma("unroll") for (int k = 0; k < 2; ++k) dst[m][k] = *(const PG8_LAS bf16x8*)(lds + PG8_SA(b, h) + aoff + m * 2048 + k * 1024); } while (0)
; #define PG8_LDB(dst, b, h) do { _Pragma("unroll") for (int n = 0; n < 2; ++n) _Pragma("unroll") for (int k = 0; k < 2; ++k) dst[n][k] = *(const PG8_LAS bf16x8*)(lds + PG8_SB(b, h) + boff + n * 2048 + k * 1024); } while (0)
; #define PG8_MMA(ai, bj, At, Bt) do { __builtin_amdgcn_s_setprio(1); _Pragma("unroll") for (int m = 0; m < 4; ++m) _Pragma("unroll") for (int n = 0; n < 2; ++n) _Pragma("unroll") for (int k = 0; k < 2; ++k) \
;         acc[ai][bj][m][n] = __builtin_amdgcn_mfma_f32_16x16x32_bf16(Bt[n][k], At[m][k], acc[ai][bj][m][n], 0, 0, 0); __builtin_amdgcn_s_setprio(0); } while (0)
; #define PG8_WAIT_V(n) asm volatile("s_waitcnt vmcnt(" #n ")" ::: "memory")
; #define PG8_WAIT_L(n) asm volatile("s_waitcnt lgkmcnt(" #n ")" ::: "memory")
; #define PG8_BAR __builtin_amdgcn_s_barrier()
; #define PG8_SCHED __builtin_amdgcn_sched_barrier(0)
; template <class Epi, class Sched, bool ALIGN_EPI = false, bool SP2 = false>
; __device__ __forceinline__ void gemm_phase(PG8_LAS unsigned char* lds, const Gemm g, const Sched& S, const Epi& E, const int wid_s) {
;     ...
;             PG8_WAIT_V(8); PG8_WAIT_L(0); PG8_BAR; PG8_MMA(1, 0, At, B0); PG8_MMA(1, 1, At, B1); PG8_BAR; PG8_SCHED;
;             PG8_LDB(B0, 1, 0); PG8_LDB(B1, 1, 1); PG8_SCHED; PG8_LDA(At, 1, 0); PG8_STAGE(PG8_SA(0, 1), a2 + hstepA, voffA);
;             PG8_WAIT_V(8); PG8_WAIT_L(0); PG8_BAR; PG8_MMA(0, 0, At, B0); PG8_MMA(0, 1, At, B1); PG8_BAR; PG8_SCHED;
	s_setprio 1
	s_waitcnt lgkmcnt(0)
	v_mfma_f32_16x16x32_bf16 v[64:67], v[132:135], v[194:197], v[64:67]
	v_mfma_f32_16x16x32_bf16 v[60:63], v[140:143], v[194:197], v[60:63]
	v_mfma_f32_16x16x32_bf16 v[48:51], v[132:135], v[202:205], v[48:51]
	v_mfma_f32_16x16x32_bf16 v[44:47], v[140:143], v[202:205], v[44:47]
	v_mfma_f32_16x16x32_bf16 v[32:35], v[132:135], v[210:213], v[32:35]
	v_mfma_f32_16x16x32_bf16 v[28:31], v[140:143], v[210:213], v[28:31]
	v_mfma_f32_16x16x32_bf16 v[16:19], v[132:135], v[218:221], v[16:19]
	v_mfma_f32_16x16x32_bf16 v[12:15], v[140:143], v[218:221], v[12:15]
	v_mfma_f32_16x16x32_bf16 v[64:67], v[136:139], v[198:201], v[64:67]
	v_mfma_f32_16x16x32_bf16 v[60:63], v[144:147], v[198:201], v[60:63]
	v_mfma_f32_16x16x32_bf16 v[48:51], v[136:139], v[206:209], v[48:51]
	v_mfma_f32_16x16x32_bf16 v[44:47], v[144:147], v[206:209], v[44:47]
	v_mfma_f32_16x16x32_bf16 v[32:35], v[136:139], v[214:217], v[32:35]
	v_mfma_f32_16x16x32_bf16 v[28:31], v[144:147], v[214:217], v[28:31]
	v_mfma_f32_16x16x32_bf16 v[16:19], v[136:139], v[222:225], v[16:19]
	v_mfma_f32_16x16x32_bf16 v[12:15], v[144:147], v[222:225], v[12:15]
	s_setprio 0
	s_setprio 1
	v_mfma_f32_16x16x32_bf16 v[56:59], v[148:151], v[194:197], v[56:59]
	v_mfma_f32_16x16x32_bf16 v[52:55], v[156:159], v[194:197], v[52:55]
	v_mfma_f32_16x16x32_bf16 v[40:43], v[148:151], v[202:205], v[40:43]
	v_mfma_f32_16x16x32_bf16 v[36:39], v[156:159], v[202:205], v[36:39]
	v_mfma_f32_16x16x32_bf16 v[24:27], v[148:151], v[210:213], v[24:27]
	v_mfma_f32_16x16x32_bf16 v[20:23], v[156:159], v[210:213], v[20:23]
	v_mfma_f32_16x16x32_bf16 v[8:11], v[148:151], v[218:221], v[8:11]
	v_mfma_f32_16x16x32_bf16 v[2:5], v[156:159], v[218:221], v[4:7]
	v_mfma_f32_16x16x32_bf16 v[56:59], v[152:155], v[198:201], v[56:59]
	v_mfma_f32_16x16x32_bf16 v[52:55], v[182:185], v[198:201], v[52:55]
	v_mfma_f32_16x16x32_bf16 v[40:43], v[152:155], v[206:209], v[40:43]
	v_mfma_f32_16x16x32_bf16 v[36:39], v[182:185], v[206:209], v[36:39]
	v_mfma_f32_16x16x32_bf16 v[24:27], v[152:155], v[214:217], v[24:27]
	v_mfma_f32_16x16x32_bf16 v[20:23], v[182:185], v[214:217], v[20:23]
	v_mfma_f32_16x16x32_bf16 v[8:11], v[152:155], v[222:225], v[8:11]
	v_mfma_f32_16x16x32_bf16 v[2:5], v[182:185], v[222:225], v[2:5]
	s_setprio 0
	s_barrier
	s_add_i32 s76, 0, 0x18000
	v_add_u32_e32 v1, s76, v189
	s_add_i32 s77, 0, 0x1c000
	ds_read_b128 v[132:135], v1
	ds_read_b128 v[136:139], v1 offset:1024
	ds_read_b128 v[140:143], v1 offset:2048
	ds_read_b128 v[144:147], v1 offset:3072
	v_add_u32_e32 v1, s77, v189
	ds_read_b128 v[148:151], v1
	ds_read_b128 v[152:155], v1 offset:1024
	ds_read_b128 v[156:159], v1 offset:2048
	ds_read_b128 v[182:185], v1 offset:3072
	s_add_u32 s48, s48, 0x60000
	s_addc_u32 s49, s49, 0
	s_mov_b32 m0, s53
	ds_read_b128 v[194:197], v192 offset:32768
	ds_read_b128 v[198:201], v192 offset:33792
	ds_read_b128 v[202:205], v192 offset:34816
	ds_read_b128 v[206:209], v192 offset:35840
	ds_read_b128 v[210:213], v192 offset:36864
	ds_read_b128 v[214:217], v192 offset:37888
	ds_read_b128 v[218:221], v192 offset:38912
	ds_read_b128 v[222:225], v192 offset:39936
	global_load_lds_dwordx4 v162, s[48:49]
	s_mov_b32 m0, s54
	s_nop 0
	global_load_lds_dwordx4 v166, s[48:49]
	s_waitcnt vmcnt(8)
	s_waitcnt lgkmcnt(0)
	s_barrier
	s_setprio 1
	s_waitcnt lgkmcnt(0)
	v_mfma_f32_16x16x32_bf16 v[128:131], v[132:135], v[194:197], v[128:131]
	v_mfma_f32_16x16x32_bf16 v[124:127], v[140:143], v[194:197], v[124:127]
	v_mfma_f32_16x16x32_bf16 v[112:115], v[132:135], v[202:205], v[112:115]
	v_mfma_f32_16x16x32_bf16 v[108:111], v[140:143], v[202:205], v[108:111]
	v_mfma_f32_16x16x32_bf16 v[96:99], v[132:135], v[210:213], v[96:99]
	v_mfma_f32_16x16x32_bf16 v[92:95], v[140:143], v[210:213], v[92:95]
	v_mfma_f32_16x16x32_bf16 v[80:83], v[132:135], v[218:221], v[80:83]
	v_mfma_f32_16x16x32_bf16 v[76:79], v[140:143], v[218:221], v[76:79]
	v_mfma_f32_16x16x32_bf16 v[128:131], v[136:139], v[198:201], v[128:131]
	v_mfma_f32_16x16x32_bf16 v[124:127], v[144:147], v[198:201], v[124:127]
	v_mfma_f32_16x16x32_bf16 v[112:115], v[136:139], v[206:209], v[112:115]
	v_mfma_f32_16x16x32_bf16 v[108:111], v[144:147], v[206:209], v[108:111]
	v_mfma_f32_16x16x32_bf16 v[96:99], v[136:139], v[214:217], v[96:99]
	v_mfma_f32_16x16x32_bf16 v[92:95], v[144:147], v[214:217], v[92:95]
	v_mfma_f32_16x16x32_bf16 v[80:83], v[136:139], v[222:225], v[80:83]
	v_mfma_f32_16x16x32_bf16 v[76:79], v[144:147], v[222:225], v[76:79]
	s_setprio 0
	s_setprio 1
	v_mfma_f32_16x16x32_bf16 v[120:123], v[148:151], v[194:197], v[120:123]
	v_mfma_f32_16x16x32_bf16 v[116:119], v[156:159], v[194:197], v[116:119]
	v_mfma_f32_16x16x32_bf16 v[104:107], v[148:151], v[202:205], v[104:107]
	v_mfma_f32_16x16x32_bf16 v[100:103], v[156:159], v[202:205], v[100:103]
	v_mfma_f32_16x16x32_bf16 v[88:91], v[148:151], v[210:213], v[88:91]
	v_mfma_f32_16x16x32_bf16 v[84:87], v[156:159], v[210:213], v[84:87]
	v_mfma_f32_16x16x32_bf16 v[72:75], v[148:151], v[218:221], v[72:75]
	v_mfma_f32_16x16x32_bf16 v[68:71], v[156:159], v[218:221], v[68:71]
	v_mfma_f32_16x16x32_bf16 v[120:123], v[152:155], v[198:201], v[120:123]
	v_mfma_f32_16x16x32_bf16 v[116:119], v[182:185], v[198:201], v[116:119]
	v_mfma_f32_16x16x32_bf16 v[104:107], v[152:155], v[206:209], v[104:107]
	v_mfma_f32_16x16x32_bf16 v[100:103], v[182:185], v[206:209], v[100:103]
	v_mfma_f32_16x16x32_bf16 v[88:91], v[152:155], v[214:217], v[88:91]
	v_mfma_f32_16x16x32_bf16 v[84:87], v[182:185], v[214:217], v[84:87]
	v_mfma_f32_16x16x32_bf16 v[72:75], v[152:155], v[222:225], v[72:75]
	v_mfma_f32_16x16x32_bf16 v[68:71], v[182:185], v[222:225], v[68:71]
	s_setprio 0
	s_barrier
; #define PG8_STAGE(bufoff, gbase, voff) do { _Pragma("unroll") for (int _i = 0; _i < 2; ++_i) \
;         __builtin_amdgcn_global_load_lds((const unsigned*)((const char*)(gbase) + (voff)[_i]), (PG8_LAS unsigned*)(lds + (bufoff) + ldsw + _i * 8192), 16, 0, 0); } while (0)
; #define PG8_LDA(dst, b, h) do { _Pragma("unroll") for (int m = 0; m < 4; ++m) _Pragma("unroll") for (int k = 0; k < 2; ++k) dst[m][k] = *(const PG8_LAS bf16x8*)(lds + PG8_SA(b, h) + aoff + m * 2048 + k * 1024); } while (0)
; #define PG8_MMA(ai, bj, At, Bt) do { __builtin_amdgcn_s_setprio(1); _Pragma("unroll") for (int m = 0; m < 4; ++m) _Pragma("unroll") for (int n = 0; n < 2; ++n) _Pragma("unroll") for (int k = 0; k < 2; ++k) \
;         acc[ai][bj][m][n] = __builtin_amdgcn_mfma_f32_16x16x32_bf16(Bt[n][k], At[m][k], acc[ai][bj][m][n], 0, 0, 0); __builtin_amdgcn_s_setprio(0); } while (0)
; #define PG8_WAIT_V(n) asm volatile("s_waitcnt vmcnt(" #n ")" ::: "memory")
; #define PG8_WAIT_L(n) asm volatile("s_waitcnt lgkmcnt(" #n ")" ::: "memory")
; #define PG8_BAR __builtin_amdgcn_s_barrier()
; #define PG8_SCHED __builtin_amdgcn_sched_barrier(0)
; template <class Epi, class Sched, bool ALIGN_EPI = false, bool SP2 = false>
; __device__ __forceinline__ void gemm_phase(PG8_LAS unsigned char* lds, const Gemm g, const Sched& S, const Epi& E, const int wid_s) {
;     ...
;             PG8_LDA(At, 1, 1); PG8_STAGE(PG8_SB(1, 0), b3, voffB); PG8_STAGE(PG8_SB(1, 1), b3 + hstepB, voffB); PG8_STAGE(PG8_SA(1, 0), a3, voffA);
;             PG8_WAIT_V(8); PG8_WAIT_L(0); PG8_BAR; PG8_MMA(1, 0, At, B0); PG8_MMA(1, 1, At, B1); PG8_BAR; PG8_SCHED;
	s_add_i32 s48, s76, s50
	v_lshl_add_u64 v[6:7], v[160:161], 0, s[18:19]
	s_mov_b32 m0, s48
	ds_read_b128 v[194:197], v192 offset:49152
	ds_read_b128 v[198:201], v192 offset:50176
	ds_read_b128 v[202:205], v192 offset:51200
	ds_read_b128 v[206:209], v192 offset:52224
	ds_read_b128 v[210:213], v192 offset:53248
	ds_read_b128 v[214:217], v192 offset:54272
	ds_read_b128 v[218:221], v192 offset:55296
	ds_read_b128 v[222:225], v192 offset:56320
	global_load_lds_dwordx4 v[6:7], off
	s_add_i32 m0, s48, 0x2000
	s_add_u32 s46, s46, 0x60080
	v_lshl_add_u64 v[6:7], v[186:187], 0, s[18:19]
	s_addc_u32 s47, s47, 0
	s_add_i32 s48, s77, s50
	global_load_lds_dwordx4 v[6:7], off
	s_mov_b32 m0, s48
	s_nop 0
	global_load_lds_dwordx4 v164, s[46:47]
	s_add_i32 m0, s48, 0x2000
	s_nop 0
	global_load_lds_dwordx4 v168, s[46:47]
	v_lshl_add_u64 v[6:7], v[226:227], 0, s[18:19]
	s_mov_b32 m0, s57
	s_nop 0
	global_load_lds_dwordx4 v[6:7], off
	v_lshl_add_u64 v[6:7], v[228:229], 0, s[18:19]
	s_mov_b32 m0, s58
	s_nop 0
	global_load_lds_dwordx4 v[6:7], off
	s_waitcnt vmcnt(8)
	s_waitcnt lgkmcnt(0)
	s_barrier
	s_setprio 1
	s_waitcnt lgkmcnt(0)
	v_mfma_f32_16x16x32_bf16 v[64:67], v[132:135], v[194:197], v[64:67]
	v_mfma_f32_16x16x32_bf16 v[60:63], v[140:143], v[194:197], v[60:63]
	v_mfma_f32_16x16x32_bf16 v[48:51], v[132:135], v[202:205], v[48:51]
	v_mfma_f32_16x16x32_bf16 v[44:47], v[140:143], v[202:205], v[44:47]
	v_mfma_f32_16x16x32_bf16 v[32:35], v[132:135], v[210:213], v[32:35]
	v_mfma_f32_16x16x32_bf16 v[28:31], v[140:143], v[210:213], v[28:31]
	v_mfma_f32_16x16x32_bf16 v[16:19], v[132:135], v[218:221], v[16:19]
	v_mfma_f32_16x16x32_bf16 v[12:15], v[140:143], v[218:221], v[12:15]
	v_mfma_f32_16x16x32_bf16 v[64:67], v[136:139], v[198:201], v[64:67]
	v_mfma_f32_16x16x32_bf16 v[60:63], v[144:147], v[198:201], v[60:63]
	v_mfma_f32_16x16x32_bf16 v[48:51], v[136:139], v[206:209], v[48:51]
	v_mfma_f32_16x16x32_bf16 v[44:47], v[144:147], v[206:209], v[44:47]
	v_mfma_f32_16x16x32_bf16 v[32:35], v[136:139], v[214:217], v[32:35]
	v_mfma_f32_16x16x32_bf16 v[28:31], v[144:147], v[214:217], v[28:31]
	v_mfma_f32_16x16x32_bf16 v[16:19], v[136:139], v[222:225], v[16:19]
	v_mfma_f32_16x16x32_bf16 v[12:15], v[144:147], v[222:225], v[12:15]
	s_setprio 0
	s_setprio 1
	v_mfma_f32_16x16x32_bf16 v[56:59], v[148:151], v[194:197], v[56:59]
	v_mfma_f32_16x16x32_bf16 v[52:55], v[156:159], v[194:197], v[52:55]
	v_mfma_f32_16x16x32_bf16 v[40:43], v[148:151], v[202:205], v[40:43]
	v_mfma_f32_16x16x32_bf16 v[36:39], v[156:159], v[202:205], v[36:39]
	v_mfma_f32_16x16x32_bf16 v[24:27], v[148:151], v[210:213], v[24:27]
	v_mfma_f32_16x16x32_bf16 v[20:23], v[156:159], v[210:213], v[20:23]
	v_mfma_f32_16x16x32_bf16 v[6:9], v[148:151], v[218:221], v[8:11]
	v_mfma_f32_16x16x32_bf16 v[2:5], v[156:159], v[218:221], v[2:5]
	v_mfma_f32_16x16x32_bf16 v[56:59], v[152:155], v[198:201], v[56:59]
	v_mfma_f32_16x16x32_bf16 v[52:55], v[182:185], v[198:201], v[52:55]
	v_mfma_f32_16x16x32_bf16 v[40:43], v[152:155], v[206:209], v[40:43]
	v_mfma_f32_16x16x32_bf16 v[36:39], v[182:185], v[206:209], v[36:39]
	v_mfma_f32_16x16x32_bf16 v[24:27], v[152:155], v[214:217], v[24:27]
	v_mfma_f32_16x16x32_bf16 v[20:23], v[182:185], v[214:217], v[20:23]
	v_mfma_f32_16x16x32_bf16 v[8:11], v[152:155], v[222:225], v[6:9]
	v_mfma_f32_16x16x32_bf16 v[4:7], v[182:185], v[222:225], v[2:5]
	s_setprio 0
	s_barrier
	s_add_i32 s71, s71, 2
	s_add_u32 s38, s38, 0x100
	s_addc_u32 s39, s39, 0
	s_cmp_gt_u32 s71, 21
	s_cbranch_scc1 .LBB0_564

; #define PG8_STAGE(bufoff, gbase, voff) do { _Pragma("unroll") for (int _i = 0; _i < 2; ++_i) \
;         __builtin_amdgcn_global_load_lds((const unsigned*)((const char*)(gbase) + (voff)[_i]), (PG8_LAS unsigned*)(lds + (bufoff) + ldsw + _i * 8192), 16, 0, 0); } while (0)
; #define PG8_LDA(dst, b, h) do { _Pragma("unroll") for (int m = 0; m < 4; ++m) _Pragma("unroll") for (int k = 0; k < 2; ++k) dst[m][k] = *(const PG8_LAS bf16x8*)(lds + PG8_SA(b, h) + aoff + m * 2048 + k * 1024); } while (0)
; #define PG8_LDB(dst, b, h) do { _Pragma("unroll") for (int n = 0; n < 2; ++n) _Pragma("unroll") for (int k = 0; k < 2; ++k) dst[n][k] = *(const PG8_LAS bf16x8*)(lds + PG8_SB(b, h) + boff + n * 2048 + k * 1024); } while (0)
; #define PG8_WAIT_V(n) asm volatile("s_waitcnt vmcnt(" #n ")" ::: "memory")
; #define PG8_WAIT_L(n) asm volatile("s_waitcnt lgkmcnt(" #n ")" ::: "memory")
; #define PG8_BAR __builtin_amdgcn_s_barrier()
; #define PG8_SCHED __builtin_amdgcn_sched_barrier(0)
; template <class Epi, class Sched, bool ALIGN_EPI = false, bool SP2 = false>
; __device__ __forceinline__ void gemm_phase(PG8_LAS unsigned char* lds, const Gemm g, const Sched& S, const Epi& E, const int wid_s) {
;     ...
;         for (int t = 0; t < nt; t += 2) {
;             const bool last = (t == nt - 2);
;             const char* a1 = cA + (size_t)(t + 1) * kstep;
;             const char* a2 = last ? nA : cA + (size_t)(t + 2) * kstep; const char* b2 = last ? nB : cB + (size_t)(t + 2) * kstep;
;             const char* a3 = a2 + kstep; const char* b3 = b2 + kstep;
;             if (last && has_next) S.a_ready(nxt);
;             if constexpr (Epi::HAS_MID) { if (t == Epi::MID_T) { asm volatile("" ::: "memory"); E.mid(acc, cur, wr, wc, fr, fq); asm volatile("" ::: "memory"); } }
;             if constexpr (SP2) {
;             PG8_LDB(B0, 0, 0); PG8_LDB(B1, 0, 1); PG8_SCHED; PG8_LDA(At, 0, 0); PG8_STAGE(PG8_SA(1, 1), a1 + hstepA, voffA);
;             PG8_WAIT_V(8); PG8_WAIT_L(0); PG8_BAR; PG8_MMA(0, 0, At, B0); PG8_MMA(0, 1, At, B1); PG8_BAR; PG8_SCHED;
;             PG8_LDA(At, 0, 1); PG8_STAGE(PG8_SB(0, 0), b2, voffB); PG8_STAGE(PG8_SB(0, 1), b2 + hstepB, voffB); PG8_STAGE(PG8_SA(0, 0), a2, voffA);
;             PG8_WAIT_V(8); PG8_WAIT_L(0); PG8_BAR; PG8_MMA(1, 0, At, B0); PG8_MMA(1, 1, At, B1); PG8_BAR; PG8_SCHED;
.LBB0_643:
	ds_read_b128 v[152:155], v149
	ds_read_b128 v[156:159], v149 offset:1024
	ds_read_b128 v[160:163], v149 offset:2048
	ds_read_b128 v[164:167], v149 offset:3072
	ds_read_b128 v[168:171], v150
	ds_read_b128 v[172:175], v150 offset:1024
	ds_read_b128 v[176:179], v150 offset:2048
	ds_read_b128 v[180:183], v150 offset:3072
	s_add_u32 s4, s34, 0x100
	s_addc_u32 s5, s35, 0
	s_cmp_eq_u32 s59, 12
	s_cselect_b32 s39, s27, s5
	s_cselect_b32 s38, s26, s4
	s_cselect_b32 s37, s25, s58
	s_cselect_b32 s36, s56, s57
	v_lshl_add_u64 v[144:145], s[34:35], 0, v[136:137]
	s_add_i32 m0, s44, 0xc000
	ds_read_b128 v[184:187], v151
	ds_read_b128 v[188:191], v151 offset:1024
	ds_read_b128 v[192:195], v151 offset:2048
	ds_read_b128 v[196:199], v151 offset:3072
	ds_read_b128 v[200:203], v151 offset:4096
	ds_read_b128 v[204:207], v151 offset:5120
	ds_read_b128 v[208:211], v151 offset:6144
	ds_read_b128 v[212:215], v151 offset:7168
	global_load_lds_dwordx4 v[144:145], off
	v_lshl_add_u64 v[144:145], s[34:35], 0, v[138:139]
	s_add_i32 m0, s44, 0xe000
	s_nop 0
	global_load_lds_dwordx4 v[144:145], off
	s_waitcnt vmcnt(8)
	s_waitcnt lgkmcnt(0)
	s_barrier
	s_setprio 1
	s_waitcnt lgkmcnt(0)
	v_mfma_f32_16x16x32_bf16 v[124:127], v[152:155], v[184:187], v[124:127]
	v_mfma_f32_16x16x32_bf16 v[120:123], v[160:163], v[184:187], v[120:123]
	v_mfma_f32_16x16x32_bf16 v[116:119], v[152:155], v[192:195], v[116:119]
	v_mfma_f32_16x16x32_bf16 v[104:107], v[160:163], v[192:195], v[104:107]
	v_mfma_f32_16x16x32_bf16 v[100:103], v[152:155], v[200:203], v[100:103]
	v_mfma_f32_16x16x32_bf16 v[88:91], v[160:163], v[200:203], v[88:91]
	v_mfma_f32_16x16x32_bf16 v[84:87], v[152:155], v[208:211], v[84:87]
	v_mfma_f32_16x16x32_bf16 v[72:75], v[160:163], v[208:211], v[72:75]
	v_mfma_f32_16x16x32_bf16 v[124:127], v[156:159], v[188:191], v[124:127]
	v_mfma_f32_16x16x32_bf16 v[120:123], v[164:167], v[188:191], v[120:123]
	v_mfma_f32_16x16x32_bf16 v[116:119], v[156:159], v[196:199], v[116:119]
	v_mfma_f32_16x16x32_bf16 v[104:107], v[164:167], v[196:199], v[104:107]
	v_mfma_f32_16x16x32_bf16 v[100:103], v[156:159], v[204:207], v[100:103]
	v_mfma_f32_16x16x32_bf16 v[88:91], v[164:167], v[204:207], v[88:91]
	v_mfma_f32_16x16x32_bf16 v[84:87], v[156:159], v[212:215], v[84:87]
	v_mfma_f32_16x16x32_bf16 v[72:75], v[164:167], v[212:215], v[72:75]
	s_setprio 0
	s_setprio 1
	v_mfma_f32_16x16x32_bf16 v[112:115], v[168:171], v[184:187], v[112:115]
	v_mfma_f32_16x16x32_bf16 v[108:111], v[176:179], v[184:187], v[108:111]
	v_mfma_f32_16x16x32_bf16 v[96:99], v[168:171], v[192:195], v[96:99]
	v_mfma_f32_16x16x32_bf16 v[92:95], v[176:179], v[192:195], v[92:95]
	v_mfma_f32_16x16x32_bf16 v[80:83], v[168:171], v[200:203], v[80:83]
	v_mfma_f32_16x16x32_bf16 v[76:79], v[176:179], v[200:203], v[76:79]
	v_mfma_f32_16x16x32_bf16 v[68:71], v[168:171], v[208:211], v[68:71]
	v_mfma_f32_16x16x32_bf16 v[64:67], v[176:179], v[208:211], v[64:67]
	v_mfma_f32_16x16x32_bf16 v[112:115], v[172:175], v[188:191], v[112:115]
	v_mfma_f32_16x16x32_bf16 v[108:111], v[180:183], v[188:191], v[108:111]
	v_mfma_f32_16x16x32_bf16 v[96:99], v[172:175], v[196:199], v[96:99]
	v_mfma_f32_16x16x32_bf16 v[92:95], v[180:183], v[196:199], v[92:95]
	v_mfma_f32_16x16x32_bf16 v[80:83], v[172:175], v[204:207], v[80:83]
	v_mfma_f32_16x16x32_bf16 v[76:79], v[180:183], v[204:207], v[76:79]
	v_mfma_f32_16x16x32_bf16 v[68:71], v[172:175], v[212:215], v[68:71]
	v_mfma_f32_16x16x32_bf16 v[64:67], v[180:183], v[212:215], v[64:67]
	s_setprio 0
	s_barrier
	s_add_i32 s34, s51, s33
	v_lshl_add_u64 v[144:145], s[36:37], 0, v[130:131]
	s_mov_b32 m0, s34
	ds_read_b128 v[184:187], v151 offset:16384
	ds_read_b128 v[188:191], v151 offset:17408
	ds_read_b128 v[192:195], v151 offset:18432
	ds_read_b128 v[196:199], v151 offset:19456
	ds_read_b128 v[200:203], v151 offset:20480
	ds_read_b128 v[204:207], v151 offset:21504
	ds_read_b128 v[208:211], v151 offset:22528
	ds_read_b128 v[212:215], v151 offset:23552
	global_load_lds_dwordx4 v[144:145], off
	s_add_i32 m0, s34, 0x2000
	s_add_u32 s34, s36, 0x40000
	v_lshl_add_u64 v[216:217], s[36:37], 0, v[134:135]
	s_addc_u32 s35, s37, 0
	s_add_i32 s60, s52, s33
	global_load_lds_dwordx4 v[216:217], off
	s_mov_b32 m0, s60
	v_lshl_add_u64 v[220:221], s[38:39], 0, v[132:133]
	global_load_lds_dwordx4 v130, s[34:35]
	s_add_i32 m0, s60, 0x2000
	s_nop 0
	global_load_lds_dwordx4 v134, s[34:35]
	v_lshl_add_u64 v[218:219], s[38:39], 0, v[128:129]
	s_mov_b32 m0, s44
	s_nop 0
	global_load_lds_dwordx4 v[218:219], off
	s_mov_b32 m0, s45
	s_nop 0
	global_load_lds_dwordx4 v[220:221], off
	s_waitcnt vmcnt(8)
	s_waitcnt lgkmcnt(0)
	s_barrier
; #define PG8_STAGE(bufoff, gbase, voff) do { _Pragma("unroll") for (int _i = 0; _i < 2; ++_i) \
;         __builtin_amdgcn_global_load_lds((const unsigned*)((const char*)(gbase) + (voff)[_i]), (PG8_LAS unsigned*)(lds + (bufoff) + ldsw + _i * 8192), 16, 0, 0); } while (0)
; #define PG8_LDA(dst, b, h) do { _Pragma("unroll") for (int m = 0; m < 4; ++m) _Pragma("unroll") for (int k = 0; k < 2; ++k) dst[m][k] = *(const PG8_LAS bf16x8*)(lds + PG8_SA(b, h) + aoff + m * 2048 + k * 1024); } while (0)
; #define PG8_LDB(dst, b, h) do { _Pragma("unroll") for (int n = 0; n < 2; ++n) _Pragma("unroll") for (int k = 0; k < 2; ++k) dst[n][k] = *(const PG8_LAS bf16x8*)(lds + PG8_SB(b, h) + boff + n * 2048 + k * 1024); } while (0)
; #define PG8_MMA(ai, bj, At, Bt) do { __builtin_amdgcn_s_setprio(1); _Pragma("unroll") for (int m = 0; m < 4; ++m) _Pragma("unroll") for (int n = 0; n < 2; ++n) _Pragma("unroll") for (int k = 0; k < 2; ++k) \
;         acc[ai][bj][m][n] = __builtin_amdgcn_mfma_f32_16x16x32_bf16(Bt[n][k], At[m][k], acc[ai][bj][m][n], 0, 0, 0); __builtin_amdgcn_s_setprio(0); } while (0)
; #define PG8_WAIT_V(n) asm volatile("s_waitcnt vmcnt(" #n ")" ::: "memory")
; #define PG8_WAIT_L(n) asm volatile("s_waitcnt lgkmcnt(" #n ")" ::: "memory")
; #define PG8_BAR __builtin_amdgcn_s_barrier()
; #define PG8_SCHED __builtin_amdgcn_sched_barrier(0)
; template <class Epi, class Sched, bool ALIGN_EPI = false, bool SP2 = false>
; __device__ __forceinline__ void gemm_phase(PG8_LAS unsigned char* lds, const Gemm g, const Sched& S, const Epi& E, const int wid_s) {
;     ...
;             PG8_WAIT_V(8); PG8_WAIT_L(0); PG8_BAR; PG8_MMA(1, 0, At, B0); PG8_MMA(1, 1, At, B1); PG8_BAR; PG8_SCHED;
;             PG8_LDB(B0, 1, 0); PG8_LDB(B1, 1, 1); PG8_SCHED; PG8_LDA(At, 1, 0); PG8_STAGE(PG8_SA(0, 1), a2 + hstepA, voffA);
;             PG8_WAIT_V(8); PG8_WAIT_L(0); PG8_BAR; PG8_MMA(0, 0, At, B0); PG8_MMA(0, 1, At, B1); PG8_BAR; PG8_SCHED;
	s_setprio 1
	s_waitcnt lgkmcnt(0)
	v_mfma_f32_16x16x32_bf16 v[60:63], v[152:155], v[184:187], v[60:63]
	v_mfma_f32_16x16x32_bf16 v[56:59], v[160:163], v[184:187], v[56:59]
	v_mfma_f32_16x16x32_bf16 v[52:55], v[152:155], v[192:195], v[52:55]
	v_mfma_f32_16x16x32_bf16 v[40:43], v[160:163], v[192:195], v[40:43]
	v_mfma_f32_16x16x32_bf16 v[36:39], v[152:155], v[200:203], v[36:39]
	v_mfma_f32_16x16x32_bf16 v[24:27], v[160:163], v[200:203], v[24:27]
	v_mfma_f32_16x16x32_bf16 v[20:23], v[152:155], v[208:211], v[20:23]
	v_mfma_f32_16x16x32_bf16 v[8:11], v[160:163], v[208:211], v[8:11]
	v_mfma_f32_16x16x32_bf16 v[60:63], v[156:159], v[188:191], v[60:63]
	v_mfma_f32_16x16x32_bf16 v[56:59], v[164:167], v[188:191], v[56:59]
	v_mfma_f32_16x16x32_bf16 v[52:55], v[156:159], v[196:199], v[52:55]
	v_mfma_f32_16x16x32_bf16 v[40:43], v[164:167], v[196:199], v[40:43]
	v_mfma_f32_16x16x32_bf16 v[36:39], v[156:159], v[204:207], v[36:39]
	v_mfma_f32_16x16x32_bf16 v[24:27], v[164:167], v[204:207], v[24:27]
	v_mfma_f32_16x16x32_bf16 v[20:23], v[156:159], v[212:215], v[20:23]
	v_mfma_f32_16x16x32_bf16 v[8:11], v[164:167], v[212:215], v[8:11]
	s_setprio 0
	s_setprio 1
	v_mfma_f32_16x16x32_bf16 v[48:51], v[168:171], v[184:187], v[48:51]
	v_mfma_f32_16x16x32_bf16 v[44:47], v[176:179], v[184:187], v[44:47]
	v_mfma_f32_16x16x32_bf16 v[32:35], v[168:171], v[192:195], v[32:35]
	v_mfma_f32_16x16x32_bf16 v[28:31], v[176:179], v[192:195], v[28:31]
	v_mfma_f32_16x16x32_bf16 v[16:19], v[168:171], v[200:203], v[16:19]
	v_mfma_f32_16x16x32_bf16 v[12:15], v[176:179], v[200:203], v[12:15]
	v_mfma_f32_16x16x32_bf16 v[4:7], v[168:171], v[208:211], v[4:7]
	v_mfma_f32_16x16x32_bf16 v[0:3], v[176:179], v[208:211], v[0:3]
	v_mfma_f32_16x16x32_bf16 v[48:51], v[172:175], v[188:191], v[48:51]
	v_mfma_f32_16x16x32_bf16 v[44:47], v[180:183], v[188:191], v[44:47]
	v_mfma_f32_16x16x32_bf16 v[32:35], v[172:175], v[196:199], v[32:35]
	v_mfma_f32_16x16x32_bf16 v[28:31], v[180:183], v[196:199], v[28:31]
	v_mfma_f32_16x16x32_bf16 v[16:19], v[172:175], v[204:207], v[16:19]
	v_mfma_f32_16x16x32_bf16 v[12:15], v[180:183], v[204:207], v[12:15]
	v_mfma_f32_16x16x32_bf16 v[4:7], v[172:175], v[212:215], v[4:7]
	v_mfma_f32_16x16x32_bf16 v[0:3], v[180:183], v[212:215], v[0:3]
	s_setprio 0
	s_barrier
	s_add_i32 s60, 0, 0x18000
	s_add_i32 s61, 0, 0x1c000
	v_add_u32_e32 v164, s60, v147
	v_add_u32_e32 v180, s61, v147
	ds_read_b128 v[152:155], v164
	ds_read_b128 v[156:159], v164 offset:1024
	ds_read_b128 v[160:163], v164 offset:2048
	ds_read_b128 v[164:167], v164 offset:3072
	ds_read_b128 v[168:171], v180
	ds_read_b128 v[172:175], v180 offset:1024
	ds_read_b128 v[176:179], v180 offset:2048
	ds_read_b128 v[180:183], v180 offset:3072
	s_add_u32 s34, s38, 0x104000
	s_addc_u32 s35, s39, 0
	s_mov_b32 m0, s46
	ds_read_b128 v[184:187], v151 offset:32768
	ds_read_b128 v[188:191], v151 offset:33792
	ds_read_b128 v[192:195], v151 offset:34816
	ds_read_b128 v[196:199], v151 offset:35840
	ds_read_b128 v[200:203], v151 offset:36864
	ds_read_b128 v[204:207], v151 offset:37888
	ds_read_b128 v[208:211], v151 offset:38912
	ds_read_b128 v[212:215], v151 offset:39936
	global_load_lds_dwordx4 v128, s[34:35]
	v_lshl_add_u64 v[222:223], s[34:35], 0, v[132:133]
	s_mov_b32 m0, s47
	s_nop 0
	global_load_lds_dwordx4 v[222:223], off
	s_waitcnt vmcnt(8)
	s_waitcnt lgkmcnt(0)
	s_barrier
	s_setprio 1
	s_waitcnt lgkmcnt(0)
	v_mfma_f32_16x16x32_bf16 v[124:127], v[152:155], v[184:187], v[124:127]
	v_mfma_f32_16x16x32_bf16 v[120:123], v[160:163], v[184:187], v[120:123]
	v_mfma_f32_16x16x32_bf16 v[116:119], v[152:155], v[192:195], v[116:119]
	v_mfma_f32_16x16x32_bf16 v[104:107], v[160:163], v[192:195], v[104:107]
	v_mfma_f32_16x16x32_bf16 v[100:103], v[152:155], v[200:203], v[100:103]
	v_mfma_f32_16x16x32_bf16 v[88:91], v[160:163], v[200:203], v[88:91]
	v_mfma_f32_16x16x32_bf16 v[84:87], v[152:155], v[208:211], v[84:87]
	v_mfma_f32_16x16x32_bf16 v[72:75], v[160:163], v[208:211], v[72:75]
	v_mfma_f32_16x16x32_bf16 v[124:127], v[156:159], v[188:191], v[124:127]
	v_mfma_f32_16x16x32_bf16 v[120:123], v[164:167], v[188:191], v[120:123]
	v_mfma_f32_16x16x32_bf16 v[116:119], v[156:159], v[196:199], v[116:119]
	v_mfma_f32_16x16x32_bf16 v[104:107], v[164:167], v[196:199], v[104:107]
	v_mfma_f32_16x16x32_bf16 v[100:103], v[156:159], v[204:207], v[100:103]
	v_mfma_f32_16x16x32_bf16 v[88:91], v[164:167], v[204:207], v[88:91]
	v_mfma_f32_16x16x32_bf16 v[84:87], v[156:159], v[212:215], v[84:87]
	v_mfma_f32_16x16x32_bf16 v[72:75], v[164:167], v[212:215], v[72:75]
	s_setprio 0
	s_setprio 1
	v_mfma_f32_16x16x32_bf16 v[112:115], v[168:171], v[184:187], v[112:115]
	v_mfma_f32_16x16x32_bf16 v[108:111], v[176:179], v[184:187], v[108:111]
	v_mfma_f32_16x16x32_bf16 v[96:99], v[168:171], v[192:195], v[96:99]
	v_mfma_f32_16x16x32_bf16 v[92:95], v[176:179], v[192:195], v[92:95]
	v_mfma_f32_16x16x32_bf16 v[80:83], v[168:171], v[200:203], v[80:83]
	v_mfma_f32_16x16x32_bf16 v[76:79], v[176:179], v[200:203], v[76:79]
	v_mfma_f32_16x16x32_bf16 v[68:71], v[168:171], v[208:211], v[68:71]
	v_mfma_f32_16x16x32_bf16 v[64:67], v[176:179], v[208:211], v[64:67]
	v_mfma_f32_16x16x32_bf16 v[112:115], v[172:175], v[188:191], v[112:115]
	v_mfma_f32_16x16x32_bf16 v[108:111], v[180:183], v[188:191], v[108:111]
	v_mfma_f32_16x16x32_bf16 v[96:99], v[172:175], v[196:199], v[96:99]
	v_mfma_f32_16x16x32_bf16 v[92:95], v[180:183], v[196:199], v[92:95]
	v_mfma_f32_16x16x32_bf16 v[80:83], v[172:175], v[204:207], v[80:83]
	v_mfma_f32_16x16x32_bf16 v[76:79], v[180:183], v[204:207], v[76:79]
	v_mfma_f32_16x16x32_bf16 v[68:71], v[172:175], v[212:215], v[68:71]
	v_mfma_f32_16x16x32_bf16 v[64:67], v[180:183], v[212:215], v[64:67]
	s_setprio 0
	s_barrier
; #define PG8_STAGE(bufoff, gbase, voff) do { _Pragma("unroll") for (int _i = 0; _i < 2; ++_i) \
;         __builtin_amdgcn_global_load_lds((const unsigned*)((const char*)(gbase) + (voff)[_i]), (PG8_LAS unsigned*)(lds + (bufoff) + ldsw + _i * 8192), 16, 0, 0); } while (0)
; #define PG8_LDA(dst, b, h) do { _Pragma("unroll") for (int m = 0; m < 4; ++m) _Pragma("unroll") for (int k = 0; k < 2; ++k) dst[m][k] = *(const PG8_LAS bf16x8*)(lds + PG8_SA(b, h) + aoff + m * 2048 + k * 1024); } while (0)
; #define PG8_MMA(ai, bj, At, Bt) do { __builtin_amdgcn_s_setprio(1); _Pragma("unroll") for (int m = 0; m < 4; ++m) _Pragma("unroll") for (int n = 0; n < 2; ++n) _Pragma("unroll") for (int k = 0; k < 2; ++k) \
;         acc[ai][bj][m][n] = __builtin_amdgcn_mfma_f32_16x16x32_bf16(Bt[n][k], At[m][k], acc[ai][bj][m][n], 0, 0, 0); __builtin_amdgcn_s_setprio(0); } while (0)
; #define PG8_WAIT_V(n) asm volatile("s_waitcnt vmcnt(" #n ")" ::: "memory")
; #define PG8_WAIT_L(n) asm volatile("s_waitcnt lgkmcnt(" #n ")" ::: "memory")
; #define PG8_BAR __builtin_amdgcn_s_barrier()
; #define PG8_SCHED __builtin_amdgcn_sched_barrier(0)
; template <class Epi, class Sched, bool ALIGN_EPI = false, bool SP2 = false>
; __device__ __forceinline__ void gemm_phase(PG8_LAS unsigned char* lds, const Gemm g, const Sched& S, const Epi& E, const int wid_s) {
;     ...
;         for (int t = 0; t < nt; t += 2) {
;             const bool last = (t == nt - 2);
;     ...
;             PG8_LDA(At, 1, 1); PG8_STAGE(PG8_SB(1, 0), b3, voffB); PG8_STAGE(PG8_SB(1, 1), b3 + hstepB, voffB); PG8_STAGE(PG8_SA(1, 0), a3, voffA);
;             PG8_WAIT_V(8); PG8_WAIT_L(0); PG8_BAR; PG8_MMA(1, 0, At, B0); PG8_MMA(1, 1, At, B1); PG8_BAR; PG8_SCHED;
	s_add_i32 s34, s60, s33
	v_lshl_add_u64 v[144:145], v[144:145], 0, s[8:9]
	s_mov_b32 m0, s34
	ds_read_b128 v[184:187], v151 offset:49152
	ds_read_b128 v[188:191], v151 offset:50176
	ds_read_b128 v[192:195], v151 offset:51200
	ds_read_b128 v[196:199], v151 offset:52224
	ds_read_b128 v[200:203], v151 offset:53248
	ds_read_b128 v[204:207], v151 offset:54272
	ds_read_b128 v[208:211], v151 offset:55296
	ds_read_b128 v[212:215], v151 offset:56320
	global_load_lds_dwordx4 v[144:145], off
	s_add_i32 m0, s34, 0x2000
	s_add_u32 s34, s36, 0x40080
	v_lshl_add_u64 v[144:145], v[216:217], 0, s[8:9]
	s_addc_u32 s35, s37, 0
	s_add_i32 s36, s61, s33
	global_load_lds_dwordx4 v[144:145], off
	s_mov_b32 m0, s36
	s_nop 0
	global_load_lds_dwordx4 v130, s[34:35]
	s_add_i32 m0, s36, 0x2000
	s_nop 0
	global_load_lds_dwordx4 v134, s[34:35]
	v_lshl_add_u64 v[144:145], v[218:219], 0, s[8:9]
	s_mov_b32 m0, s49
	s_nop 0
	global_load_lds_dwordx4 v[144:145], off
	v_lshl_add_u64 v[144:145], v[220:221], 0, s[8:9]
	s_mov_b32 m0, s50
	s_nop 0
	global_load_lds_dwordx4 v[144:145], off
	s_waitcnt vmcnt(8)
	s_waitcnt lgkmcnt(0)
	s_barrier
	s_setprio 1
	s_waitcnt lgkmcnt(0)
	v_mfma_f32_16x16x32_bf16 v[60:63], v[152:155], v[184:187], v[60:63]
	v_mfma_f32_16x16x32_bf16 v[56:59], v[160:163], v[184:187], v[56:59]
	v_mfma_f32_16x16x32_bf16 v[52:55], v[152:155], v[192:195], v[52:55]
	v_mfma_f32_16x16x32_bf16 v[40:43], v[160:163], v[192:195], v[40:43]
	v_mfma_f32_16x16x32_bf16 v[36:39], v[152:155], v[200:203], v[36:39]
	v_mfma_f32_16x16x32_bf16 v[24:27], v[160:163], v[200:203], v[24:27]
	v_mfma_f32_16x16x32_bf16 v[20:23], v[152:155], v[208:211], v[20:23]
	v_mfma_f32_16x16x32_bf16 v[8:11], v[160:163], v[208:211], v[8:11]
	v_mfma_f32_16x16x32_bf16 v[60:63], v[156:159], v[188:191], v[60:63]
	v_mfma_f32_16x16x32_bf16 v[56:59], v[164:167], v[188:191], v[56:59]
	v_mfma_f32_16x16x32_bf16 v[52:55], v[156:159], v[196:199], v[52:55]
	v_mfma_f32_16x16x32_bf16 v[40:43], v[164:167], v[196:199], v[40:43]
	v_mfma_f32_16x16x32_bf16 v[36:39], v[156:159], v[204:207], v[36:39]
	v_mfma_f32_16x16x32_bf16 v[24:27], v[164:167], v[204:207], v[24:27]
	v_mfma_f32_16x16x32_bf16 v[20:23], v[156:159], v[212:215], v[20:23]
	v_mfma_f32_16x16x32_bf16 v[8:11], v[164:167], v[212:215], v[8:11]
	s_setprio 0
	s_setprio 1
	v_mfma_f32_16x16x32_bf16 v[48:51], v[168:171], v[184:187], v[48:51]
	v_mfma_f32_16x16x32_bf16 v[44:47], v[176:179], v[184:187], v[44:47]
	v_mfma_f32_16x16x32_bf16 v[32:35], v[168:171], v[192:195], v[32:35]
	v_mfma_f32_16x16x32_bf16 v[28:31], v[176:179], v[192:195], v[28:31]
	v_mfma_f32_16x16x32_bf16 v[16:19], v[168:171], v[200:203], v[16:19]
	v_mfma_f32_16x16x32_bf16 v[12:15], v[176:179], v[200:203], v[12:15]
	v_mfma_f32_16x16x32_bf16 v[4:7], v[168:171], v[208:211], v[4:7]
	v_mfma_f32_16x16x32_bf16 v[0:3], v[176:179], v[208:211], v[0:3]
	v_mfma_f32_16x16x32_bf16 v[48:51], v[172:175], v[188:191], v[48:51]
	v_mfma_f32_16x16x32_bf16 v[44:47], v[180:183], v[188:191], v[44:47]
	v_mfma_f32_16x16x32_bf16 v[32:35], v[172:175], v[196:199], v[32:35]
	v_mfma_f32_16x16x32_bf16 v[28:31], v[180:183], v[196:199], v[28:31]
	v_mfma_f32_16x16x32_bf16 v[16:19], v[172:175], v[204:207], v[16:19]
	v_mfma_f32_16x16x32_bf16 v[12:15], v[180:183], v[204:207], v[12:15]
	v_mfma_f32_16x16x32_bf16 v[4:7], v[172:175], v[212:215], v[4:7]
	v_mfma_f32_16x16x32_bf16 v[0:3], v[180:183], v[212:215], v[0:3]
	s_setprio 0
	s_barrier
	s_add_i32 s59, s59, 2
	s_add_u32 s57, s57, 0x100
	s_addc_u32 s58, s58, 0
	s_cmp_gt_u32 s59, 13
	s_mov_b64 s[34:35], s[4:5]
	s_cbranch_scc0 .LBB0_643
	s_and_b64 vcc, exec, s[10:11]
	s_cbranch_vccz .LBB0_646
	s_barrier
